# attention unit prologues: MLA first-tile loads no longer drained before the k_pe loads; MoBA query loads for block selection issued as one group
# baseline (speedup 1.0000x reference)
; DI int tid_opaque() { int t = threadIdx.x; asm volatile("" : "+v"(t)); return t; }
; DI float bf_lo(unsigned u) { return __uint_as_float(u << 16); }
; DI float bf_hi(unsigned u) { return __uint_as_float(u & 0xffff0000u); }
; template <int MODE>
; DI void attn_unit(unsigned char* ws, int b, int h, int qb, LAS unsigned char* lds, bool do_store = true) {
;     ...
;     const int tid = tid_opaque(), lane = tid & 63, w = __builtin_amdgcn_readfirstlane(tid >> 6), r = lane & 31, hh = lane >> 5;
;     const int q0 = qb * 256; const long rowbase = (long)b * SEQ;
;     const int qg = q0 + 32 * w + r;
;     bf16x8 qf[NS];
;     { const bf16_t* qrow = Qb + (size_t)(rowbase + qg) * QPITCH + qcol + 8 * hh;
; #pragma unroll
;       for (int s = 0; s < NS; ++s) qf[s] = *(const bf16x8*)(qrow + 16 * s); }
;     unsigned mysel = 0;
;     if (MODE == 2) {
;         if (tid < 256) {
;             const bf16_t* qr = Qb + (size_t)(rowbase + q0 + tid) * QPITCH + qcol;
;             float qv[64];
; #pragma unroll
;             for (int c8 = 0; c8 < 8; ++c8) { const u32x4 u = *(const u32x4*)(qr + c8 * 8);
; #pragma unroll
;                 for (int e = 0; e < 4; ++e) { qv[c8 * 8 + 2 * e] = bf_lo(u[e]); qv[c8 * 8 + 2 * e + 1] = bf_hi(u[e]); } }
.LBB0_124:
	s_and_b64 vcc, exec, s[38:39]
	s_cbranch_vccz .LBB0_95
	s_ashr_i32 s46, s14, 7
	s_sub_i32 s30, 15, s46
	s_and_b32 s31, s14, 63
	s_and_b32 s2, s14, 64
	s_lshl_b32 s15, s30, 8
	s_cmp_lg_u32 s2, 0
	s_mov_b64 s[38:39], -1
	s_cbranch_scc0 .LBB0_174
	v_mov_b32_e32 v14, v210
	s_lshr_b32 s44, s31, 3
	v_readfirstlane_b32 s38, v14
	s_ashr_i32 s53, s38, 1
	s_andn2_b32 s53, s53, 31
	v_and_b32_e32 v28, 31, v14
	s_add_i32 s52, s53, s15
	s_waitcnt vmcnt(0)
	v_or_b32_e32 v158, s52, v28
	s_lshl_b32 s2, s44, 12
	v_ashrrev_i32_e32 v159, 31, v158
	v_lshl_add_u64 v[2:3], v[158:159], 0, s[2:3]
	v_mov_b64_e32 v[4:5], s[20:21]
	s_and_b32 s45, s14, 7
	v_mad_u64_u32 v[4:5], s[38:39], v2, s88, v[4:5]
	v_bfe_u32 v29, v14, 5, 1
	v_mad_i32_i24 v5, v3, s88, v5
	s_lshl_b32 s38, s45, 7
	s_mov_b32 s39, s3
	v_lshl_add_u64 v[156:157], v[4:5], 0, s[38:39]
	v_lshlrev_b32_e32 v0, 4, v29
	v_lshl_add_u64 v[2:3], v[156:157], 0, v[0:1]
	global_load_dwordx4 v[82:85], v[2:3], off
	global_load_dwordx4 v[86:89], v[2:3], off offset:32
	global_load_dwordx4 v[90:93], v[2:3], off offset:64
	global_load_dwordx4 v[94:97], v[2:3], off offset:96
	s_movk_i32 s38, 0xff
	v_cmp_lt_i32_e32 vcc, s38, v14
	v_lshlrev_b32_e32 v30, 2, v14
	s_and_saveexec_b64 s[38:39], vcc
	s_xor_b64 s[38:39], exec, s[38:39]
	v_lshlrev_b32_e32 v30, 2, v14
	s_or_saveexec_b64 s[38:39], s[38:39]
	s_lshl_b32 s54, s45, 6
	s_xor_b64 exec, exec, s[38:39]
	s_cbranch_execz .LBB0_140
	v_mov_b32_e32 v4, -1
	s_cmp_eq_u32 s46, 15
	v_mov_b32_e32 v3, -1
	v_mov_b32_e32 v98, -1
	s_cbranch_scc1 .LBB0_139
	s_add_i32 s46, s15, s2
	s_mov_b32 s47, s3
	v_ashrrev_i32_e32 v15, 31, v14
	v_lshl_add_u64 v[2:3], v[14:15], 0, s[46:47]
	v_mov_b64_e32 v[4:5], s[20:21]
	v_mad_u64_u32 v[4:5], s[46:47], v2, s88, v[4:5]
	v_mad_i32_i24 v5, v3, s88, v5
	s_lshl_b32 s46, s54, 1
	s_mov_b32 s47, s3
	v_lshl_add_u64 v[20:21], v[4:5], 0, s[46:47]
	global_load_dwordx4 v[2:5], v[20:21], off offset:48
	global_load_dwordx4 v[6:9], v[20:21], off offset:32
	global_load_dwordx4 v[10:13], v[20:21], off offset:16
	global_load_dwordx4 v[16:19], v[20:21], off
	global_load_dwordx4 v[180:183], v[20:21], off offset:112
	global_load_dwordx4 v[184:187], v[20:21], off offset:96
	global_load_dwordx4 v[188:191], v[20:21], off offset:80
	global_load_dwordx4 v[192:195], v[20:21], off offset:64
	s_lshl_b32 s45, s45, 12
	s_lshl_b32 s44, s44, 15
	s_or_b32 s44, s44, s45
	s_add_u32 s44, s9, s44
	s_addc_u32 s45, s13, 0
	s_mov_b32 s55, 0
	v_mov_b32_e32 v102, -1
	v_mov_b32_e32 v100, 0xff800000
	v_mov_b32_e32 v101, 0xff800000
	v_mov_b32_e32 v103, 0xff800000
	v_mov_b32_e32 v99, -1
	v_mov_b32_e32 v98, -1
	s_waitcnt vmcnt(7)
	v_lshlrev_b32_e32 v54, 16, v2
	s_waitcnt vmcnt(6)
	v_lshlrev_b32_e32 v46, 16, v6
	s_waitcnt vmcnt(5)
	v_lshlrev_b32_e32 v38, 16, v10
	s_waitcnt vmcnt(4)
	v_lshlrev_b32_e32 v15, 16, v16
	v_and_b32_e32 v31, 0xffff0000, v16
	v_lshlrev_b32_e32 v32, 16, v17
	v_and_b32_e32 v33, 0xffff0000, v17
	v_lshlrev_b32_e32 v34, 16, v18
	v_and_b32_e32 v35, 0xffff0000, v18
	v_lshlrev_b32_e32 v36, 16, v19
	v_and_b32_e32 v37, 0xffff0000, v19
	v_and_b32_e32 v39, 0xffff0000, v10
	v_lshlrev_b32_e32 v40, 16, v11
	v_and_b32_e32 v41, 0xffff0000, v11
	v_lshlrev_b32_e32 v42, 16, v12
	v_and_b32_e32 v43, 0xffff0000, v12
	v_lshlrev_b32_e32 v44, 16, v13
	v_and_b32_e32 v45, 0xffff0000, v13
	v_and_b32_e32 v47, 0xffff0000, v6
	v_lshlrev_b32_e32 v48, 16, v7
	v_and_b32_e32 v49, 0xffff0000, v7
	v_lshlrev_b32_e32 v50, 16, v8
	v_and_b32_e32 v51, 0xffff0000, v8
	v_lshlrev_b32_e32 v52, 16, v9
	v_and_b32_e32 v53, 0xffff0000, v9
	v_and_b32_e32 v55, 0xffff0000, v2
	v_lshlrev_b32_e32 v56, 16, v3
	v_and_b32_e32 v57, 0xffff0000, v3
	v_lshlrev_b32_e32 v58, 16, v4
	v_and_b32_e32 v59, 0xffff0000, v4
	v_lshlrev_b32_e32 v60, 16, v5
	v_and_b32_e32 v61, 0xffff0000, v5
	s_waitcnt vmcnt(3)
	v_lshlrev_b32_e32 v20, 16, v180
	s_waitcnt vmcnt(2)
	v_lshlrev_b32_e32 v78, 16, v184
	s_waitcnt vmcnt(1)
	v_lshlrev_b32_e32 v70, 16, v188
	s_waitcnt vmcnt(0)
	v_lshlrev_b32_e32 v62, 16, v192
	v_and_b32_e32 v63, 0xffff0000, v192
	v_lshlrev_b32_e32 v64, 16, v193
	v_and_b32_e32 v65, 0xffff0000, v193
	v_lshlrev_b32_e32 v66, 16, v194
	v_and_b32_e32 v67, 0xffff0000, v194
	v_lshlrev_b32_e32 v68, 16, v195
	v_and_b32_e32 v69, 0xffff0000, v195
	v_and_b32_e32 v71, 0xffff0000, v188
	v_lshlrev_b32_e32 v72, 16, v189
	v_and_b32_e32 v73, 0xffff0000, v189
	v_lshlrev_b32_e32 v74, 16, v190
	v_and_b32_e32 v75, 0xffff0000, v190
	v_lshlrev_b32_e32 v76, 16, v191
	v_and_b32_e32 v77, 0xffff0000, v191
	v_and_b32_e32 v79, 0xffff0000, v184
	v_lshlrev_b32_e32 v80, 16, v185
	v_and_b32_e32 v81, 0xffff0000, v185
	v_lshlrev_b32_e32 v16, 16, v186
	v_and_b32_e32 v17, 0xffff0000, v186
	v_lshlrev_b32_e32 v18, 16, v187
	v_and_b32_e32 v19, 0xffff0000, v187
	v_and_b32_e32 v21, 0xffff0000, v180
	v_lshlrev_b32_e32 v22, 16, v181
	v_and_b32_e32 v23, 0xffff0000, v181
	v_lshlrev_b32_e32 v24, 16, v182
	v_and_b32_e32 v25, 0xffff0000, v182
	v_lshlrev_b32_e32 v26, 16, v183
	v_and_b32_e32 v27, 0xffff0000, v183

; #define LAS __attribute__((address_space(3)))
; template <int MODE>
; DI void attn_unit(unsigned char* ws, int b, int h, int qb, LAS unsigned char* lds, bool do_store = true) {
;     ...
;     const int qcol = MODE == 0 ? h * 96 : h * 64, kcol = MODE == 0 ? h * 128 : 512 + h * 64, vcol = MODE == 0 ? h * 128 + 64 : 1024 + h * 64, ocol = h * 64;
;     const int tid = tid_opaque(), lane = tid & 63, w = __builtin_amdgcn_readfirstlane(tid >> 6), r = lane & 31, hh = lane >> 5;
;     const int q0 = qb * 256; const long rowbase = (long)b * SEQ;
;     const int qg = q0 + 32 * w + r;
;     bf16x8 qf[NS];
;     { const bf16_t* qrow = Qb + (size_t)(rowbase + qg) * QPITCH + qcol + 8 * hh;
; #pragma unroll
;       for (int s = 0; s < NS; ++s) qf[s] = *(const bf16x8*)(qrow + 16 * s); }
;     unsigned mysel = 0;
;     if (MODE == 2) {
;         if (tid < 256) {
;             const bf16_t* qr = Qb + (size_t)(rowbase + q0 + tid) * QPITCH + qcol;
;             float qv[64];
; #pragma unroll
;             for (int c8 = 0; c8 < 8; ++c8) { const u32x4 u = *(const u32x4*)(qr + c8 * 8);
; #pragma unroll
;                 for (int e = 0; e < 4; ++e) { qv[c8 * 8 + 2 * e] = bf_lo(u[e]); qv[c8 * 8 + 2 * e + 1] = bf_hi(u[e]); } }
;             const float* km = (const float*)(ws + WS_KMEAN) + (size_t)((b * 8 + h) * 16) * 64;
;             float v0 = -INFINITY, v1 = -INFINITY, v2 = -INFINITY; int i0 = -1, i1 = -1, i2 = -1;
;             for (int n = 0; n < qb; ++n) { float d = 0.f;
; #pragma unroll
;                 for (int e = 0; e < 64; ++e) d += qv[e] * km[n * 64 + e];
;                 if (d > v0) { v2 = v1; i2 = i1; v1 = v0; i1 = i0; v0 = d; i0 = n; }
;                 else if (d > v1) { v2 = v1; i2 = i1; v1 = d; i1 = n; }
;                 else if (d > v2) { v2 = d; i2 = n; } }
;             unsigned mk = 0; if (i0 >= 0) mk |= 1u << i0; if (i1 >= 0) mk |= 1u << i1; if (i2 >= 0) mk |= 1u << i2;
;             *(LAS unsigned*)(lds + AT_SEL + tid * 4) = mk;
;         }
;         __syncthreads();
;         mysel = *(LAS unsigned*)(lds + AT_SEL + (32 * w + r) * 4);
;     }
;     const int kkey = tid >> 3, kch = tid & 7, pkey = (tid & 255) >> 2, pch = tid & 3;
;     u32x4 kr[2], vr[2], pr[2];
;     pr[0] = (u32x4){0u, 0u, 0u, 0u}; pr[1] = pr[0];
;     ...
;     const int kt_hi = qb * 4 + 3;
;     AT_LOADG(kt_hi, 0); AT_LOADG(kt_hi - 1, 1); AT_STORE(0, 0);
.LBB0_174:
	s_and_b64 vcc, exec, s[38:39]
	s_cbranch_vccz .LBB0_95
	v_mov_b32_e32 v3, v210
	s_and_b32 s48, s14, 7
	v_readfirstlane_b32 s2, v3
	s_lshl_b32 s14, s31, 9
	s_ashr_i32 s2, s2, 1
	s_and_b32 s38, s14, 0x7000
	s_and_b32 s14, s2, 0xffffffe0
	v_and_b32_e32 v4, 31, v3
	s_add_i32 s14, s14, s15
	v_or_b32_e32 v178, s14, v4
	s_mov_b32 s39, s3
	v_ashrrev_i32_e32 v179, 31, v178
	v_lshl_add_u64 v[176:177], v[178:179], 0, s[38:39]
	v_mov_b64_e32 v[6:7], s[22:23]
	v_mad_u64_u32 v[6:7], s[44:45], v176, s7, v[6:7]
	v_mad_i32_i24 v7, v177, s7, v7
	s_mul_i32 s2, s48, 0xc0
	v_lshl_add_u64 v[6:7], v[6:7], 0, s[2:3]
	s_lshl_b32 s2, s30, 2
	s_or_b32 s30, s2, 3
	v_bfe_u32 v5, v3, 5, 1
	v_ashrrev_i32_e32 v182, 3, v3
	s_lshl_b32 s2, s30, 6
	v_lshlrev_b32_e32 v180, 4, v5
	v_mov_b32_e32 v181, v1
	s_add_i32 s2, s2, s38
	v_ashrrev_i32_e32 v183, 31, v182
	v_lshl_add_u64 v[6:7], v[6:7], 0, v[180:181]
	v_lshl_add_u64 v[8:9], v[182:183], 0, s[2:3]
	global_load_dwordx4 v[96:99], v[6:7], off
	global_load_dwordx4 v[100:103], v[6:7], off offset:32
	global_load_dwordx4 v[104:107], v[6:7], off offset:64
	global_load_dwordx4 v[108:111], v[6:7], off offset:96
	global_load_dwordx4 v[112:115], v[6:7], off offset:128
	global_load_dwordx4 v[116:119], v[6:7], off offset:160
	v_lshlrev_b64 v[8:9], 11, v[8:9]
	v_and_b32_e32 v7, 7, v3
	v_lshl_add_u64 v[8:9], s[24:25], 0, v[8:9]
	s_lshl_b32 s44, s48, 8
	s_mov_b32 s45, s3
	v_lshl_add_u64 v[8:9], v[8:9], 0, s[44:45]
	v_lshlrev_b32_e32 v16, 4, v7
	v_mov_b32_e32 v17, v1
	v_lshl_add_u64 v[8:9], v[8:9], 0, v[16:17]
	global_load_dwordx4 v[120:123], v[8:9], off
	global_load_dwordx4 v[124:127], v[8:9], off offset:128
	s_movk_i32 s31, 0xff
	v_mov_b32_e32 v130, v1
	v_mov_b32_e32 v131, v1
	v_and_b32_e32 v6, 3, v3
	v_cmp_lt_i32_e32 vcc, s31, v3
	s_movk_i32 s31, 0x100
	v_mov_b32_e32 v128, v1
	v_mov_b32_e32 v129, v1
	v_mov_b64_e32 v[134:135], v[130:131]
	v_bfe_u32 v184, v3, 2, 6
	v_cmp_gt_i32_e64 s[44:45], s31, v3
	v_lshlrev_b32_e32 v2, 4, v6
	v_mov_b64_e32 v[132:133], v[128:129]
	s_and_saveexec_b64 s[46:47], s[44:45]
	s_cbranch_execz .LBB0_177
	v_or_b32_e32 v0, s2, v184
	v_lshlrev_b64 v[8:9], 6, v[0:1]
	v_lshl_add_u64 v[8:9], s[26:27], 0, v[8:9]
	v_lshlrev_b32_e32 v0, 4, v6
	v_lshl_add_u64 v[8:9], v[8:9], 0, v[0:1]
	global_load_dwordx4 v[132:135], v[8:9], off
